# S5 pass-2 12-tasks-per-workgroup mapping now guarded by gridDim.x == 256 with the original strided loop as fallback (same code path on MI355X)
# baseline (speedup 1.0000x reference)
.LBB0_177:
	v_readlane_b32 s4, v255, 29
	s_lshl_b32 s6, s4, 3
	s_cmp_eq_u32 s33, 0x100
	s_cbranch_scc0 .Ls5_gen0
	s_mul_i32 s6, s4, 12
.Ls5_gen0:
	v_readlane_b32 s4, v253, 8
	s_add_i32 s4, s6, s4
	s_cmpk_gt_i32 s4, 0xbff
	s_cbranch_scc1 .LBB0_188
	v_ashrrev_i32_e32 v4, 5, v168
	v_lshlrev_b32_e32 v108, 3, v4
	v_readlane_b32 s8, v253, 4
	v_and_b32_e32 v167, 31, v168
	v_ashrrev_i32_e32 v109, 31, v108
	v_readlane_b32 s9, v253, 5
	v_lshlrev_b32_e32 v160, 5, v167
	v_and_b32_e32 v169, 15, v168
	s_waitcnt lgkmcnt(0)
	v_lshl_add_u64 v[0:1], v[108:109], 1, s[8:9]
	v_readlane_b32 s8, v253, 2
	v_ashrrev_i32_e32 v5, 4, v168
	v_lshl_add_u64 v[110:111], v[0:1], 0, v[160:161]
	v_lshlrev_b32_e32 v160, 8, v169
	v_readlane_b32 s9, v253, 3
	v_lshlrev_b32_e32 v2, 3, v5
	v_ashrrev_i32_e32 v3, 31, v2
	v_lshl_add_u64 v[0:1], s[8:9], 0, v[160:161]
	s_mul_i32 s8, s18, 0x300
	s_ashr_i32 s9, s8, 31
	s_mov_b32 s10, s18
	s_mov_b32 s7, s27
	v_readlane_b32 s12, v252, 3
	v_lshl_add_u64 v[112:113], v[2:3], 1, v[0:1]
	s_lshl_b64 s[8:9], s[8:9], 2
	v_readlane_b32 s22, v252, 13
	v_xor_b32_e32 v0, 32, v220
	v_readlane_b32 s23, v252, 14
	v_readlane_b32 s27, v252, 18
	s_add_u32 s8, s22, s8
	v_lshlrev_b32_e32 v114, 2, v5
	v_cmp_lt_i32_e32 vcc, v0, v221
	s_mov_b32 s27, s7
	s_addc_u32 s9, s23, s9
	v_ashrrev_i32_e32 v115, 31, v114
	v_cndmask_b32_e32 v0, v220, v0, vcc
	v_lshlrev_b32_e32 v160, 2, v167
	v_readlane_b32 s7, v253, 10
	v_and_b32_e32 v1, -16, v168
	v_lshl_add_u64 v[116:117], v[114:115], 2, s[8:9]
	v_lshlrev_b32_e32 v234, 2, v0
	v_add_u32_e32 v0, s7, v160
	v_add_u32_e32 v1, s7, v1
	v_readlane_b32 s8, v252, 40
	s_movk_i32 s7, 0x440
	v_readlane_b32 s9, v252, 41
	v_mul_lo_u32 v2, v4, s7
	v_readlane_b32 s7, v253, 8
	v_readlane_b32 s20, v252, 11
	v_readlane_b32 s21, v252, 12
	v_lshl_add_u64 v[118:119], v[114:115], 1, s[8:9]
	s_add_i32 s8, s6, s7
	v_readlane_b32 s6, v254, 39
	v_readlane_b32 s18, v252, 9
	v_readlane_b32 s20, v255, 17
	v_mul_u32_u24_e32 v3, 0x110, v169
	v_readlane_b32 s7, v254, 40
	s_mov_b32 s18, s10
	v_readlane_b32 s21, v255, 18
	v_cmp_gt_u32_e64 s[36:37], 32, v168
	v_lshl_add_u64 v[120:121], s[6:7], 0, v[160:161]
	v_add_u32_e32 v235, v0, v2
	v_add_u32_e32 v236, v1, v3
	v_readlane_b32 s13, v252, 4
	v_readlane_b32 s14, v252, 5
	v_readlane_b32 s15, v252, 6
	v_readlane_b32 s16, v252, 7
	v_readlane_b32 s17, v252, 8
	v_readlane_b32 s19, v252, 10
	v_readlane_b32 s24, v252, 15
	v_readlane_b32 s25, v252, 16
	v_readlane_b32 s26, v252, 17

.LBB0_185:
	v_or_b32_e32 v204, s11, v239
	v_cndmask_b32_e64 v0, 0, 1, s[6:7]
	v_ashrrev_i32_e32 v205, 31, v204
	v_cmp_ne_u32_e32 vcc, 1, v0
	v_lshlrev_b64 v[0:1], 11, v[204:205]
	v_or_b32_e32 v200, 16, v204
	v_lshl_add_u64 v[0:1], v[146:147], 0, v[0:1]
	v_ashrrev_i32_e32 v201, 31, v200
	global_load_dwordx2 v[206:207], v[0:1], off
	v_lshlrev_b64 v[0:1], 11, v[200:201]
	v_lshl_add_u64 v[0:1], v[146:147], 0, v[0:1]
	global_load_dwordx2 v[202:203], v[0:1], off
	s_waitcnt vmcnt(2)
	v_cndmask_b32_e64 v3, v107, v103, s[6:7]
	v_cndmask_b32_e64 v2, v106, v102, s[6:7]
	v_cndmask_b32_e64 v1, v105, v101, s[6:7]
	v_cndmask_b32_e64 v0, v104, v100, s[6:7]
	s_mov_b32 s11, 32
	s_and_b64 vcc, exec, vcc
	v_mfma_f32_32x32x16_bf16 v[32:47], v[0:3], v[72:75], 0
	v_mfma_f32_32x32x16_bf16 v[48:63], v[0:3], v[64:67], 0
	s_nop 10
	v_mul_f32_e64 v162, v190, v32
	v_mul_f32_e64 v163, v191, v32
	v_mov_b32_e32 v223, v34
	v_mfma_f32_32x32x16_bf16 v[16:31], v[0:3], v[68:71], 0
	v_fma_f32 v164, v126, v48, -v162
	v_fma_f32 v165, v127, v49, -v163
	v_fma_f32 v162, v126, v48, v162
	v_fma_f32 v163, v127, v48, v163
	v_mov_b32_e32 v222, v50
	v_mov_b32_e32 v165, v163
	v_mov_b32_e32 v162, v49
	v_mov_b32_e32 v163, v33
	v_pk_add_f32 v[162:163], v[162:163], v[164:165]
	v_mov_b32_e32 v34, v51
	v_mul_f32_e32 v208, v128, v162
	v_pk_fma_f32 v[210:211], v[128:129], v[162:163], v[208:209] op_sel_hi:[1,1,0]
	v_pk_mul_f32 v[208:209], v[190:191], v[36:37] op_sel_hi:[1,0]
	v_mul_f32_e32 v164, v127, v163
	v_pk_fma_f32 v[212:213], v[126:127], v[52:53], v[208:209] neg_lo:[0,0,1] neg_hi:[0,0,1]
	v_pk_fma_f32 v[208:209], v[126:127], v[52:53], v[208:209] op_sel_hi:[1,0,1]
	v_pk_fma_f32 v[164:165], v[126:127], v[162:163], v[164:165] op_sel_hi:[1,1,0] neg_lo:[0,0,1] neg_hi:[0,0,1]
	v_mov_b32_e32 v213, v209
	v_mov_b32_e32 v208, v53
	v_mov_b32_e32 v209, v37
	v_pk_add_f32 v[208:209], v[208:209], v[212:213]
	v_mov_b32_e32 v165, v211
	v_mul_f32_e32 v210, v127, v209
	v_pk_fma_f32 v[212:213], v[126:127], v[208:209], v[210:211] op_sel_hi:[1,1,0] neg_lo:[0,0,1] neg_hi:[0,0,1]
	v_mul_f32_e32 v210, v128, v208
	v_pk_add_f32 v[164:165], v[222:223], v[164:165]
	v_pk_fma_f32 v[214:215], v[128:129], v[208:209], v[210:211] op_sel_hi:[1,1,0]
	v_pk_mul_f32 v[210:211], v[158:159], v[164:165]
	v_mov_b32_e32 v49, v32
	v_pk_fma_f32 v[222:223], v[156:157], v[164:165], v[210:211] op_sel:[0,0,1] op_sel_hi:[1,1,0] neg_lo:[0,0,1] neg_hi:[0,0,1]
	v_pk_fma_f32 v[210:211], v[156:157], v[164:165], v[210:211] op_sel:[0,0,1] op_sel_hi:[1,1,0]
	v_mov_b32_e32 v213, v215
	v_mov_b32_e32 v223, v211
	v_pk_add_f32 v[34:35], v[34:35], v[222:223]
	ds_bpermute_b32 v37, v234, v34
	ds_bpermute_b32 v53, v234, v35
	v_pk_mul_f32 v[210:211], v[154:155], v[196:197] op_sel_hi:[1,0]
	v_mfma_f32_32x32x16_bf16 v[0:15], v[0:3], v[76:79], 0
	v_fma_f32 v222, v150, v198, -v210
	v_fma_f32 v223, v151, v199, -v211
	v_fma_f32 v210, v150, v198, v210
	v_fma_f32 v211, v151, v198, v211
	s_waitcnt lgkmcnt(0)
	v_cndmask_b32_e64 v51, v53, v35, s[36:37]
	v_cndmask_b32_e64 v50, v37, v34, s[36:37]
	v_mov_b32_e32 v223, v211
	v_pk_add_f32 v[50:51], v[222:223], v[50:51]
	s_nop 0
	v_cndmask_b32_e64 v199, v51, v196, s[36:37]
	v_cndmask_b32_e64 v198, v50, v198, s[36:37]
	v_pk_fma_f32 v[32:33], v[156:157], v[198:199], v[48:49]
	v_pk_mul_f32 v[48:49], v[158:159], v[198:199]
	s_nop 0
	v_pk_add_f32 v[210:211], v[32:33], v[48:49] op_sel:[0,1] op_sel_hi:[1,0] neg_lo:[0,1] neg_hi:[0,1]
	v_pk_add_f32 v[32:33], v[32:33], v[48:49] op_sel:[0,1] op_sel_hi:[1,0]
	v_pk_mul_f32 v[48:49], v[172:173], v[198:199]
	v_cvt_pk_bf16_f32 v245, v210, v33
	v_pk_fma_f32 v[32:33], v[170:171], v[198:199], v[162:163]
	s_nop 0
	v_pk_add_f32 v[162:163], v[32:33], v[48:49] op_sel:[0,1] op_sel_hi:[1,0] neg_lo:[0,1] neg_hi:[0,1]
	v_pk_add_f32 v[32:33], v[32:33], v[48:49] op_sel:[0,1] op_sel_hi:[1,0]
	v_pk_mul_f32 v[48:49], v[138:139], v[198:199]
	v_cvt_pk_bf16_f32 v244, v162, v33
	v_pk_fma_f32 v[32:33], v[136:137], v[198:199], v[164:165]
	s_nop 0
	v_pk_add_f32 v[162:163], v[32:33], v[48:49] op_sel:[0,1] op_sel_hi:[1,0] neg_lo:[0,1] neg_hi:[0,1]
	v_pk_add_f32 v[32:33], v[32:33], v[48:49] op_sel:[0,1] op_sel_hi:[1,0]
	v_pk_mul_f32 v[48:49], v[176:177], v[198:199]
	v_cvt_pk_bf16_f32 v243, v162, v33
	v_pk_fma_f32 v[32:33], v[174:175], v[198:199], v[34:35]
	v_cndmask_b32_e64 v35, v35, v53, s[36:37]
	v_pk_add_f32 v[162:163], v[32:33], v[48:49] op_sel:[0,1] op_sel_hi:[1,0] neg_lo:[0,1] neg_hi:[0,1]
	v_pk_add_f32 v[32:33], v[32:33], v[48:49] op_sel:[0,1] op_sel_hi:[1,0]
	v_cndmask_b32_e64 v34, v34, v37, s[36:37]
	v_cvt_pk_bf16_f32 v242, v162, v33
	v_mov_b32_e32 v32, v54
	v_mov_b32_e32 v33, v38
	v_pk_add_f32 v[32:33], v[32:33], v[212:213]
	v_mov_b32_e32 v38, v55
	v_pk_mul_f32 v[48:49], v[158:159], v[32:33]
	v_mov_b32_e32 v53, v36
	v_pk_fma_f32 v[162:163], v[156:157], v[32:33], v[48:49] op_sel:[0,0,1] op_sel_hi:[1,1,0] neg_lo:[0,0,1] neg_hi:[0,0,1]
	v_pk_fma_f32 v[48:49], v[156:157], v[32:33], v[48:49] op_sel:[0,0,1] op_sel_hi:[1,1,0]
	s_nop 0
	v_mov_b32_e32 v163, v49
	v_pk_add_f32 v[198:199], v[38:39], v[162:163]
	v_pk_mul_f32 v[48:49], v[176:177], v[50:51]
	ds_bpermute_b32 v246, v234, v198
	ds_bpermute_b32 v247, v234, v199
	v_pk_fma_f32 v[54:55], v[174:175], v[50:51], v[48:49] op_sel:[0,0,1] op_sel_hi:[1,1,0] neg_lo:[0,0,1] neg_hi:[0,0,1]
	v_pk_fma_f32 v[48:49], v[174:175], v[50:51], v[48:49] op_sel:[0,0,1] op_sel_hi:[1,1,0]
	s_waitcnt lgkmcnt(1)
	v_cndmask_b32_e64 v38, v246, v198, s[36:37]
	v_mov_b32_e32 v55, v49
	v_pk_add_f32 v[34:35], v[34:35], v[54:55]
	s_waitcnt lgkmcnt(0)
	v_cndmask_b32_e64 v39, v247, v199, s[36:37]
	v_pk_mul_f32 v[48:49], v[176:177], v[34:35]
	s_nop 0
	v_pk_fma_f32 v[50:51], v[174:175], v[34:35], v[48:49] op_sel:[0,0,1] op_sel_hi:[1,1,0] neg_lo:[0,0,1] neg_hi:[0,0,1]
	v_pk_fma_f32 v[48:49], v[174:175], v[34:35], v[48:49] op_sel:[0,0,1] op_sel_hi:[1,1,0]
	s_nop 0
	v_mov_b32_e32 v51, v49
	v_pk_add_f32 v[214:215], v[38:39], v[50:51]
	s_nop 0
	v_cndmask_b32_e64 v35, v215, v35, s[36:37]
	v_cndmask_b32_e64 v34, v214, v34, s[36:37]
	v_pk_fma_f32 v[36:37], v[156:157], v[34:35], v[52:53]
	v_pk_mul_f32 v[38:39], v[158:159], v[34:35]
	v_pk_fma_f32 v[32:33], v[136:137], v[34:35], v[32:33]
	v_pk_add_f32 v[48:49], v[36:37], v[38:39] op_sel:[0,1] op_sel_hi:[1,0] neg_lo:[0,1] neg_hi:[0,1]
	v_pk_add_f32 v[36:37], v[36:37], v[38:39] op_sel:[0,1] op_sel_hi:[1,0]
	v_pk_mul_f32 v[38:39], v[172:173], v[34:35]
	v_cvt_pk_bf16_f32 v241, v48, v37
	v_pk_fma_f32 v[36:37], v[170:171], v[34:35], v[208:209]
	v_pk_mul_f32 v[224:225], v[176:177], v[214:215]
	v_pk_add_f32 v[48:49], v[36:37], v[38:39] op_sel:[0,1] op_sel_hi:[1,0] neg_lo:[0,1] neg_hi:[0,1]
	v_pk_add_f32 v[36:37], v[36:37], v[38:39] op_sel:[0,1] op_sel_hi:[1,0]
	v_pk_fma_f32 v[226:227], v[174:175], v[214:215], v[224:225] op_sel:[0,0,1] op_sel_hi:[1,1,0] neg_lo:[0,0,1] neg_hi:[0,0,1]
	v_cvt_pk_bf16_f32 v240, v48, v37
	v_pk_mul_f32 v[36:37], v[138:139], v[34:35]
	v_pk_fma_f32 v[214:215], v[174:175], v[214:215], v[224:225] op_sel:[0,0,1] op_sel_hi:[1,1,0]
	v_pk_add_f32 v[38:39], v[32:33], v[36:37] op_sel:[0,1] op_sel_hi:[1,0] neg_lo:[0,1] neg_hi:[0,1]
	v_pk_add_f32 v[32:33], v[32:33], v[36:37] op_sel:[0,1] op_sel_hi:[1,0]
	v_mov_b32_e32 v227, v215
	v_cvt_pk_bf16_f32 v205, v38, v33
	v_pk_fma_f32 v[32:33], v[174:175], v[34:35], v[198:199]
	v_pk_mul_f32 v[34:35], v[176:177], v[34:35]
	v_cndmask_b32_e64 v199, v199, v247, s[36:37]
	v_pk_add_f32 v[36:37], v[32:33], v[34:35] op_sel:[0,1] op_sel_hi:[1,0] neg_lo:[0,1] neg_hi:[0,1]
	v_pk_add_f32 v[32:33], v[32:33], v[34:35] op_sel:[0,1] op_sel_hi:[1,0]
	v_cndmask_b32_e64 v198, v198, v246, s[36:37]
	v_cvt_pk_bf16_f32 v201, v36, v33
	v_pk_mul_f32 v[32:33], v[192:193], v[0:1] op_sel_hi:[1,0]
	v_pk_add_f32 v[198:199], v[198:199], v[226:227]
	v_pk_fma_f32 v[34:35], v[130:131], v[16:17], v[32:33]
	v_pk_fma_f32 v[32:33], v[130:131], v[16:17], v[32:33] op_sel_hi:[1,0,1] neg_lo:[0,0,1] neg_hi:[0,0,1]
	v_mov_b32_e32 v164, v199
	v_mov_b32_e32 v35, v33
	v_mov_b32_e32 v32, v1
	v_mov_b32_e32 v33, v17
	v_pk_add_f32 v[208:209], v[32:33], v[34:35]
	v_mov_b32_e32 v162, v198
	v_pk_mul_f32 v[32:33], v[182:183], v[208:209]
	s_nop 0
	v_pk_fma_f32 v[34:35], v[184:185], v[208:209], v[32:33] op_sel:[0,0,1] op_sel_hi:[1,1,0] neg_lo:[1,0,0] neg_hi:[1,0,0]
	v_pk_fma_f32 v[32:33], v[184:185], v[208:209], v[32:33] op_sel:[0,0,1] op_sel_hi:[1,1,0]
	s_nop 0
	v_mov_b32_e32 v35, v33
	v_mov_b32_e32 v32, v18
	v_mov_b32_e32 v33, v2
	v_pk_add_f32 v[210:211], v[32:33], v[34:35]
	v_mov_b32_e32 v2, v19
	v_pk_mul_f32 v[32:33], v[184:185], v[210:211]
	s_nop 0
	v_pk_fma_f32 v[34:35], v[182:183], v[210:211], v[32:33] op_sel:[0,0,1] op_sel_hi:[1,1,0] neg_lo:[0,0,1] neg_hi:[0,0,1]
	v_pk_fma_f32 v[32:33], v[182:183], v[210:211], v[32:33] op_sel:[0,0,1] op_sel_hi:[1,1,0]
	s_nop 0
	v_mov_b32_e32 v35, v33
	v_pk_add_f32 v[212:213], v[2:3], v[34:35]
	ds_bpermute_b32 v1, v234, v212
	ds_bpermute_b32 v2, v234, v213
	v_pk_mul_f32 v[32:33], v[186:187], v[196:197] op_sel:[0,1]
	s_waitcnt lgkmcnt(1)
	v_cndmask_b32_e64 v18, v1, v212, s[36:37]
	v_pk_fma_f32 v[34:35], v[152:153], v[160:161], v[32:33] neg_lo:[0,0,1] neg_hi:[0,0,1]
	v_pk_fma_f32 v[32:33], v[152:153], v[160:161], v[32:33] op_sel_hi:[1,0,1]
	s_waitcnt lgkmcnt(0)
	v_cndmask_b32_e64 v19, v2, v213, s[36:37]
	v_mov_b32_e32 v35, v33
	v_pk_add_f32 v[18:19], v[34:35], v[18:19]
	v_cndmask_b32_e64 v3, v213, v2, s[36:37]
	v_pk_mul_f32 v[32:33], v[188:189], v[18:19]
	v_cndmask_b32_e64 v248, v18, v160, s[36:37]
	v_cndmask_b32_e64 v249, v19, v197, s[36:37]
	v_pk_fma_f32 v[34:35], v[180:181], v[18:19], v[32:33] op_sel:[0,0,1] op_sel_hi:[1,1,0] neg_lo:[0,0,1] neg_hi:[0,0,1]
	v_pk_fma_f32 v[18:19], v[180:181], v[18:19], v[32:33] op_sel:[0,0,1] op_sel_hi:[1,1,0]
	v_cndmask_b32_e64 v2, v212, v1, s[36:37]
	v_mov_b32_e32 v35, v19
	v_pk_mul_f32 v[18:19], v[194:195], v[4:5] op_sel_hi:[1,0]
	v_pk_add_f32 v[2:3], v[2:3], v[34:35]
	v_pk_fma_f32 v[32:33], v[178:179], v[20:21], v[18:19] neg_lo:[0,0,1] neg_hi:[0,0,1]
	v_pk_fma_f32 v[18:19], v[178:179], v[20:21], v[18:19] op_sel_hi:[1,0,1]
	v_fma_f32 v16, v123, v248, v16
	v_mov_b32_e32 v33, v19
	v_mov_b32_e32 v18, v21
	v_mov_b32_e32 v19, v5
	v_pk_add_f32 v[50:51], v[18:19], v[32:33]
	v_fma_f32 v0, v123, v249, v0
	v_pk_mul_f32 v[18:19], v[184:185], v[50:51]
	v_fma_f32 v16, -v125, v249, v16
	v_pk_fma_f32 v[32:33], v[182:183], v[50:51], v[18:19] op_sel:[0,0,1] op_sel_hi:[1,1,0] neg_lo:[0,0,1] neg_hi:[0,0,1]
	v_pk_fma_f32 v[18:19], v[182:183], v[50:51], v[18:19] op_sel:[0,0,1] op_sel_hi:[1,1,0]
	v_fmac_f32_e32 v0, v125, v248
	v_mov_b32_e32 v33, v19
	v_mov_b32_e32 v18, v22
	v_mov_b32_e32 v19, v6
	v_pk_add_f32 v[52:53], v[18:19], v[32:33]
	v_mov_b32_e32 v6, v23
	v_pk_mul_f32 v[18:19], v[184:185], v[52:53]
	v_cvt_pk_bf16_f32 v0, v16, v0
	v_pk_fma_f32 v[32:33], v[182:183], v[52:53], v[18:19] op_sel:[0,0,1] op_sel_hi:[1,1,0] neg_lo:[0,0,1] neg_hi:[0,0,1]
	v_pk_fma_f32 v[18:19], v[182:183], v[52:53], v[18:19] op_sel:[0,0,1] op_sel_hi:[1,1,0]
	ds_write2_b32 v235, v245, v0 offset1:32
	v_mov_b32_e32 v33, v19
	v_pk_add_f32 v[54:55], v[6:7], v[32:33]
	ds_bpermute_b32 v1, v234, v54
	ds_bpermute_b32 v5, v234, v55
	v_pk_mul_f32 v[18:19], v[188:189], v[2:3]
	v_fma_f32 v0, v133, v248, v209
	v_pk_fma_f32 v[22:23], v[180:181], v[2:3], v[18:19] op_sel:[0,0,1] op_sel_hi:[1,1,0] neg_lo:[0,0,1] neg_hi:[0,0,1]
	v_pk_fma_f32 v[18:19], v[180:181], v[2:3], v[18:19] op_sel:[0,0,1] op_sel_hi:[1,1,0]
	s_waitcnt lgkmcnt(0)
	v_cndmask_b32_e64 v7, v5, v55, s[36:37]
	v_cndmask_b32_e64 v6, v1, v54, s[36:37]
	v_mov_b32_e32 v23, v19
	v_pk_add_f32 v[6:7], v[6:7], v[22:23]
	v_cndmask_b32_e64 v1, v54, v1, s[36:37]
	v_cndmask_b32_e64 v17, v6, v2, s[36:37]
	v_cndmask_b32_e64 v21, v7, v3, s[36:37]
	v_pk_mul_f32 v[2:3], v[152:153], v[6:7]
	v_mov_b32_e32 v22, v57
	v_sub_f32_e32 v2, v2, v3
	v_add_f32_e32 v163, v1, v2
	v_pk_mul_f32 v[2:3], v[186:187], v[6:7]
	v_mov_b32_e32 v6, v40
	v_mov_b32_e32 v7, v8
	v_add_f32_e32 v1, v2, v3
	v_mov_b32_e32 v2, v56
	v_mov_b32_e32 v3, v24
	v_pk_mul_f32 v[18:19], v[124:125], v[6:7]
	v_pk_mul_f32 v[6:7], v[122:123], v[6:7]
	v_pk_fma_f32 v[18:19], v[122:123], v[2:3], v[18:19] neg_lo:[0,0,1] neg_hi:[0,0,1]
	v_pk_fma_f32 v[2:3], v[124:125], v[2:3], v[6:7]
	v_mov_b32_e32 v6, v41
	v_mov_b32_e32 v7, v9
	v_mov_b32_e32 v23, v25
	v_pk_add_f32 v[34:35], v[6:7], v[2:3]
	v_pk_add_f32 v[32:33], v[22:23], v[18:19]
	v_pk_mul_f32 v[2:3], v[124:125], v[34:35]
	v_mov_b32_e32 v6, v58
	v_pk_fma_f32 v[2:3], v[122:123], v[32:33], v[2:3] neg_lo:[0,0,1] neg_hi:[0,0,1]
	v_mov_b32_e32 v7, v26
	v_pk_add_f32 v[36:37], v[6:7], v[2:3]
	v_pk_mul_f32 v[2:3], v[124:125], v[32:33]
	v_mov_b32_e32 v6, v42
	v_pk_fma_f32 v[2:3], v[122:123], v[34:35], v[2:3]
	v_mov_b32_e32 v7, v10
	v_pk_add_f32 v[38:39], v[6:7], v[2:3]
	v_mov_b32_e32 v26, v59
	v_pk_mul_f32 v[2:3], v[124:125], v[38:39]
	v_mov_b32_e32 v10, v43
	v_pk_fma_f32 v[2:3], v[122:123], v[36:37], v[2:3] neg_lo:[0,0,1] neg_hi:[0,0,1]
	v_mov_b32_e32 v6, v44
	v_pk_add_f32 v[48:49], v[26:27], v[2:3]
	v_pk_mul_f32 v[2:3], v[124:125], v[36:37]
	v_mov_b32_e32 v7, v12
	v_pk_fma_f32 v[2:3], v[122:123], v[38:39], v[2:3]
	v_cndmask_b32_e64 v5, v55, v5, s[36:37]
	v_pk_add_f32 v[42:43], v[10:11], v[2:3]
	v_mov_b32_e32 v2, v60
	v_mov_b32_e32 v3, v28
	v_pk_mul_f32 v[10:11], v[124:125], v[6:7]
	v_pk_mul_f32 v[6:7], v[122:123], v[6:7]
	v_pk_fma_f32 v[10:11], v[122:123], v[2:3], v[10:11] neg_lo:[0,0,1] neg_hi:[0,0,1]
	v_mov_b32_e32 v18, v61
	v_mov_b32_e32 v19, v29
	v_pk_fma_f32 v[2:3], v[124:125], v[2:3], v[6:7]
	v_mov_b32_e32 v6, v45
	v_mov_b32_e32 v7, v13
	v_add_f32_e32 v165, v5, v1
	ds_bpermute_b32 v1, v234, v48
	ds_bpermute_b32 v9, v234, v49
	v_pk_add_f32 v[10:11], v[18:19], v[10:11]
	v_pk_add_f32 v[18:19], v[6:7], v[2:3]
	ds_bpermute_b32 v5, v234, v42
	ds_bpermute_b32 v25, v234, v43
	v_pk_mul_f32 v[2:3], v[124:125], v[18:19]
	v_mov_b32_e32 v6, v62
	v_pk_fma_f32 v[2:3], v[122:123], v[10:11], v[2:3] neg_lo:[0,0,1] neg_hi:[0,0,1]
	v_mov_b32_e32 v7, v30
	v_pk_add_f32 v[22:23], v[6:7], v[2:3]
	v_pk_mul_f32 v[2:3], v[124:125], v[10:11]
	v_mov_b32_e32 v6, v46
	v_pk_fma_f32 v[2:3], v[122:123], v[18:19], v[2:3]
	v_mov_b32_e32 v7, v14
	v_pk_mul_f32 v[214:215], v[142:143], v[164:165]
	s_waitcnt lgkmcnt(2)
	v_cndmask_b32_e64 v59, v9, v49, s[36:37]
	v_cndmask_b32_e64 v58, v1, v48, s[36:37]
	v_pk_add_f32 v[26:27], v[6:7], v[2:3]
	v_pk_mul_f32 v[224:225], v[142:143], v[162:163]
	v_pk_fma_f32 v[214:215], v[140:141], v[162:163], v[214:215] neg_lo:[0,0,1] neg_hi:[0,0,1]
	s_waitcnt lgkmcnt(0)
	v_cndmask_b32_e64 v197, v25, v43, s[36:37]
	v_cndmask_b32_e64 v196, v5, v42, s[36:37]
	v_pk_mul_f32 v[2:3], v[124:125], v[26:27]
	v_pk_add_f32 v[58:59], v[58:59], v[214:215]
	v_pk_fma_f32 v[214:215], v[140:141], v[164:165], v[224:225]
	v_fmac_f32_e32 v208, v133, v249
	v_pk_fma_f32 v[2:3], v[122:123], v[22:23], v[2:3] neg_lo:[0,0,1] neg_hi:[0,0,1]
	v_mov_b32_e32 v30, v63
	v_pk_mul_f32 v[6:7], v[124:125], v[22:23]
	v_pk_add_f32 v[196:197], v[196:197], v[214:215]
	v_fma_f32 v0, -v135, v249, v0
	v_fmac_f32_e32 v208, v135, v248
	v_pk_add_f32 v[2:3], v[30:31], v[2:3]
	v_pk_fma_f32 v[6:7], v[122:123], v[26:27], v[6:7]
	v_mov_b32_e32 v14, v47
	v_cndmask_b32_e64 v215, v196, v199, s[36:37]
	v_cndmask_b32_e64 v214, v58, v198, s[36:37]
	v_pk_mul_f32 v[198:199], v[142:143], v[196:197]
	v_cvt_pk_bf16_f32 v0, v0, v208
	ds_bpermute_b32 v13, v234, v2
	v_pk_add_f32 v[6:7], v[14:15], v[6:7]
	ds_bpermute_b32 v45, v234, v3
	v_cndmask_b32_e64 v15, v49, v9, s[36:37]
	v_cndmask_b32_e64 v14, v48, v1, s[36:37]
	v_pk_fma_f32 v[198:199], v[140:141], v[58:59], v[198:199] neg_lo:[0,0,1] neg_hi:[0,0,1]
	ds_write2_b32 v235, v244, v0 offset0:68 offset1:100
	v_fma_f32 v0, v237, v248, v210
	v_fmac_f32_e32 v211, v237, v249
	v_pk_add_f32 v[198:199], v[14:15], v[198:199]
	v_pk_mul_f32 v[14:15], v[140:141], v[196:197]
	v_fma_f32 v0, -v238, v249, v0
	v_fmac_f32_e32 v211, v238, v248
	ds_bpermute_b32 v29, v234, v6
	v_cndmask_b32_e64 v31, v43, v25, s[36:37]
	v_cndmask_b32_e64 v30, v42, v5, s[36:37]
	ds_bpermute_b32 v1, v234, v7
	v_pk_fma_f32 v[14:15], v[142:143], v[58:59], v[14:15]
	v_cvt_pk_bf16_f32 v0, v0, v211
	v_pk_add_f32 v[30:31], v[30:31], v[14:15]
	ds_write2_b32 v235, v243, v0 offset0:136 offset1:168
	v_fma_f32 v0, v141, v248, v212
	v_fmac_f32_e32 v213, v141, v249
	v_pk_mul_f32 v[14:15], v[142:143], v[30:31]
	v_fma_f32 v0, -v143, v249, v0
	v_fmac_f32_e32 v213, v143, v248
	s_waitcnt lgkmcnt(4)
	v_cndmask_b32_e64 v47, v45, v3, s[36:37]
	v_cndmask_b32_e64 v46, v13, v2, s[36:37]
	v_pk_fma_f32 v[14:15], v[140:141], v[198:199], v[14:15] neg_lo:[0,0,1] neg_hi:[0,0,1]
	v_cvt_pk_bf16_f32 v0, v0, v213
	v_pk_add_f32 v[46:47], v[46:47], v[14:15]
	v_pk_mul_f32 v[14:15], v[142:143], v[198:199]
	ds_write2_b32 v235, v242, v0 offset0:204 offset1:236
	v_fma_f32 v0, v123, v17, v20
	v_fma_f32 v4, v123, v21, v4
	s_waitcnt lgkmcnt(2)
	v_cndmask_b32_e64 v63, v1, v7, s[36:37]
	v_cndmask_b32_e64 v62, v29, v6, s[36:37]
	v_pk_fma_f32 v[14:15], v[140:141], v[30:31], v[14:15]
	v_fma_f32 v0, -v125, v21, v0
	v_fmac_f32_e32 v4, v125, v17
	v_pk_add_f32 v[62:63], v[62:63], v[14:15]
	v_cvt_pk_bf16_f32 v0, v0, v4
	v_add_u32_e32 v4, 0x800, v235
	v_mov_b32_e32 v14, v46
	v_mov_b32_e32 v15, v62
	ds_write2_b32 v4, v241, v0 offset0:32 offset1:64
	v_fma_f32 v0, v133, v17, v50
	v_fmac_f32_e32 v51, v133, v21
	v_cndmask_b32_e64 v223, v7, v1, s[36:37]
	v_cndmask_b32_e64 v1, v46, v198, s[36:37]
	v_cndmask_b32_e64 v30, v62, v30, s[36:37]
	v_pk_mul_f32 v[14:15], v[150:151], v[14:15]
	v_fma_f32 v0, -v135, v21, v0
	v_fmac_f32_e32 v51, v135, v17
	v_cndmask_b32_e64 v41, v2, v13, s[36:37]
	v_sub_f32_e32 v5, v14, v15
	v_fmac_f32_e32 v60, v122, v1
	v_fmac_f32_e32 v44, v122, v30
	v_cvt_pk_bf16_f32 v0, v0, v51
	v_add_f32_e32 v198, v41, v5
	v_fma_f32 v5, -v124, v30, v60
	v_fmac_f32_e32 v44, v124, v1
	ds_write2_b32 v4, v240, v0 offset0:100 offset1:132
	v_fma_f32 v0, v237, v17, v52
	v_fmac_f32_e32 v53, v237, v21
	v_cvt_pk_bf16_f32 v13, v5, v44
	v_fma_f32 v5, v132, v1, v10
	v_fma_f32 v9, v132, v30, v18
	v_fma_f32 v0, -v238, v21, v0
	v_fmac_f32_e32 v53, v238, v17
	v_fma_f32 v5, -v134, v30, v5
	v_fmac_f32_e32 v9, v134, v1
	v_cvt_pk_bf16_f32 v0, v0, v53
	v_pk_mul_f32 v[14:15], v[140:141], v[62:63]
	v_mov_b32_e32 v57, v40
	v_cvt_pk_bf16_f32 v9, v5, v9
	v_fma_f32 v5, v136, v1, v22
	v_fma_f32 v10, v136, v30, v26
	ds_write2_b32 v4, v205, v0 offset0:168 offset1:200
	v_fma_f32 v0, v141, v17, v54
	v_fmac_f32_e32 v55, v141, v21
	v_pk_fma_f32 v[224:225], v[142:143], v[46:47], v[14:15]
	v_pk_fma_f32 v[14:15], v[156:157], v[214:215], v[56:57]
	v_pk_mul_f32 v[40:41], v[158:159], v[214:215]
	v_fma_f32 v5, -v138, v30, v5
	v_fmac_f32_e32 v10, v138, v1
	v_fma_f32 v0, -v143, v21, v0
	v_fmac_f32_e32 v55, v143, v17
	v_pk_add_f32 v[56:57], v[14:15], v[40:41] op_sel:[0,1] op_sel_hi:[1,0] neg_lo:[0,1] neg_hi:[0,1]
	v_pk_add_f32 v[14:15], v[14:15], v[40:41] op_sel:[0,1] op_sel_hi:[1,0]
	v_mov_b32_e32 v40, v32
	v_mov_b32_e32 v41, v34
	v_cvt_pk_bf16_f32 v5, v5, v10
	v_cndmask_b32_e64 v10, v59, v163, s[36:37]
	v_cndmask_b32_e64 v18, v197, v165, s[36:37]
	v_cvt_pk_bf16_f32 v0, v0, v55
	v_add_u32_e32 v4, 0xa00, v235
	v_cvt_pk_bf16_f32 v15, v56, v15
	v_pk_fma_f32 v[40:41], v[170:171], v[214:215], v[40:41]
	v_pk_mul_f32 v[56:57], v[172:173], v[214:215]
	ds_write2_b32 v4, v201, v0 offset0:108 offset1:140
	v_fma_f32 v0, v123, v10, v24
	v_fma_f32 v4, v123, v18, v8
	v_pk_add_f32 v[226:227], v[40:41], v[56:57] op_sel:[0,1] op_sel_hi:[1,0] neg_lo:[0,1] neg_hi:[0,1]
	v_pk_add_f32 v[40:41], v[40:41], v[56:57] op_sel:[0,1] op_sel_hi:[1,0]
	v_fma_f32 v0, -v125, v18, v0
	v_fmac_f32_e32 v4, v125, v10
	v_cvt_pk_bf16_f32 v25, v226, v41
	v_mov_b32_e32 v40, v36
	v_mov_b32_e32 v41, v38
	v_cvt_pk_bf16_f32 v0, v0, v4
	v_add_u32_e32 v4, 0x1000, v235
	v_fmac_f32_e32 v33, v133, v10
	v_fmac_f32_e32 v35, v133, v18
	v_pk_fma_f32 v[40:41], v[136:137], v[214:215], v[40:41]
	v_pk_mul_f32 v[56:57], v[138:139], v[214:215]
	ds_write2_b32 v4, v15, v0 offset0:64 offset1:96
	v_fma_f32 v0, -v135, v18, v33
	v_fmac_f32_e32 v35, v135, v10
	v_pk_add_f32 v[226:227], v[40:41], v[56:57] op_sel:[0,1] op_sel_hi:[1,0] neg_lo:[0,1] neg_hi:[0,1]
	v_pk_add_f32 v[40:41], v[40:41], v[56:57] op_sel:[0,1] op_sel_hi:[1,0]
	v_cvt_pk_bf16_f32 v0, v0, v35
	v_fmac_f32_e32 v37, v237, v10
	v_fmac_f32_e32 v39, v237, v18
	v_cndmask_b32_e64 v222, v6, v29, s[36:37]
	v_cvt_pk_bf16_f32 v29, v226, v41
	v_mov_b32_e32 v40, v48
	v_mov_b32_e32 v41, v42
	v_fma_f32 v2, v140, v1, v2
	v_fma_f32 v6, v140, v30, v6
	ds_write2_b32 v4, v25, v0 offset0:132 offset1:164
	v_fma_f32 v0, -v238, v18, v37
	v_fmac_f32_e32 v39, v238, v10
	v_pk_fma_f32 v[40:41], v[174:175], v[214:215], v[40:41]
	v_pk_mul_f32 v[56:57], v[176:177], v[214:215]
	v_fma_f32 v2, -v142, v30, v2
	v_fmac_f32_e32 v6, v142, v1
	v_cvt_pk_bf16_f32 v0, v0, v39
	v_fmac_f32_e32 v49, v141, v10
	v_fmac_f32_e32 v43, v141, v18
	v_pk_add_f32 v[214:215], v[40:41], v[56:57] op_sel:[0,1] op_sel_hi:[1,0] neg_lo:[0,1] neg_hi:[0,1]
	v_pk_add_f32 v[40:41], v[40:41], v[56:57] op_sel:[0,1] op_sel_hi:[1,0]
	v_cvt_pk_bf16_f32 v1, v2, v6
	v_cndmask_b32_e64 v2, v47, v199, s[36:37]
	v_cndmask_b32_e64 v6, v63, v31, s[36:37]
	ds_write2_b32 v4, v29, v0 offset0:200 offset1:232
	v_fma_f32 v0, -v143, v18, v49
	v_fmac_f32_e32 v43, v143, v10
	v_cvt_pk_bf16_f32 v14, v214, v41
	v_cvt_pk_bf16_f32 v0, v0, v43
	v_add_u32_e32 v4, 0x1400, v235
	v_fmac_f32_e32 v28, v123, v2
	v_fmac_f32_e32 v12, v123, v6
	ds_write2_b32 v4, v14, v0 offset0:12 offset1:44
	v_fma_f32 v0, -v125, v6, v28
	v_fmac_f32_e32 v12, v125, v2
	v_cvt_pk_bf16_f32 v0, v0, v12
	v_add_u32_e32 v4, 0x1800, v235
	v_fmac_f32_e32 v11, v133, v2
	v_fmac_f32_e32 v19, v133, v6
	ds_write2_b32 v4, v13, v0 offset0:96 offset1:128
	v_fma_f32 v0, -v135, v6, v11
	v_fmac_f32_e32 v19, v135, v2
	v_cvt_pk_bf16_f32 v0, v0, v19
	v_fmac_f32_e32 v23, v237, v2
	v_fmac_f32_e32 v27, v237, v6
	ds_write2_b32 v4, v9, v0 offset0:164 offset1:196
	v_fma_f32 v0, -v238, v6, v23
	v_fmac_f32_e32 v27, v238, v2
	v_cndmask_b32_e64 v22, v3, v45, s[36:37]
	v_cvt_pk_bf16_f32 v0, v0, v27
	v_add_u32_e32 v4, 0x1a00, v235
	v_fmac_f32_e32 v3, v141, v2
	v_fmac_f32_e32 v7, v141, v6
	ds_write2_b32 v4, v5, v0 offset0:104 offset1:136
	v_fma_f32 v0, -v143, v6, v3
	v_fmac_f32_e32 v7, v143, v2
	v_cvt_pk_bf16_f32 v0, v0, v7
	v_add_u32_e32 v2, 0x1c00, v235
	ds_write2_b32 v2, v1, v0 offset0:44 offset1:76
	s_waitcnt lgkmcnt(0)
	ds_read_b128 v[0:3], v236
	ds_read_b128 v[4:7], v236 offset:64
	s_waitcnt lgkmcnt(1)
	v_mfma_f32_16x16x32_bf16 v[0:3], v[80:83], v[0:3], 0
	v_mov_b32_e32 v62, v47
	v_pk_mul_f32 v[30:31], v[152:153], v[62:63]
	v_pk_add_f32 v[196:197], v[222:223], v[224:225]
	s_waitcnt lgkmcnt(0)
	v_mfma_f32_16x16x32_bf16 v[0:3], v[84:87], v[4:7], v[0:3]
	ds_read_b128 v[4:7], v236 offset:128
	v_sub_f32_e32 v26, v30, v31
	v_add_f32_e32 v160, v22, v26
	s_waitcnt lgkmcnt(0)
	v_mfma_f32_16x16x32_bf16 v[0:3], v[88:91], v[4:7], v[0:3]
	ds_read_b128 v[4:7], v236 offset:192
	s_waitcnt lgkmcnt(0)
	v_mfma_f32_16x16x32_bf16 v[0:3], v[92:95], v[4:7], v[0:3]
	s_waitcnt vmcnt(1)
	v_lshlrev_b32_e32 v4, 16, v206
	v_and_b32_e32 v5, 0xffff0000, v206
	s_nop 4
	v_pk_fma_f32 v[0:1], v[96:97], v[4:5], v[0:1]
	s_nop 0
	v_mul_f32_e32 v4, 0x3d372713, v0
	v_mul_f32_e32 v5, 0x3d372713, v1
	v_mul_f32_e32 v4, v0, v4
	v_mul_f32_e32 v5, v1, v5
	v_fma_f32 v4, v0, v4, v0
	v_fma_f32 v5, v1, v5, v1
	v_mul_f32_e32 v4, 0xbfcc422a, v4
	v_mul_f32_e32 v5, 0xbfcc422a, v5
	v_mul_f32_e32 v4, 0x3fb8aa3b, v4
	v_mul_f32_e32 v5, 0x3fb8aa3b, v5
	v_exp_f32_e32 v4, v4
	v_exp_f32_e32 v5, v5
	v_add_f32_e32 v4, 1.0, v4
	v_add_f32_e32 v5, 1.0, v5
	v_rcp_f32_e32 v4, v4
	v_rcp_f32_e32 v5, v5
	s_nop 0
	v_pk_mul_f32 v[0:1], v[0:1], v[4:5]
	v_lshlrev_b32_e32 v4, 16, v207
	v_and_b32_e32 v5, 0xffff0000, v207
	v_pk_fma_f32 v[2:3], v[98:99], v[4:5], v[2:3]
	v_cvt_pk_bf16_f32 v0, v0, v1
	v_mul_f32_e32 v4, 0x3d372713, v2
	v_mul_f32_e32 v5, 0x3d372713, v3
	v_mul_f32_e32 v4, v2, v4
	v_mul_f32_e32 v5, v3, v5
	v_fma_f32 v4, v2, v4, v2
	v_fma_f32 v5, v3, v5, v3
	v_mul_f32_e32 v4, 0xbfcc422a, v4
	v_mul_f32_e32 v5, 0xbfcc422a, v5
	v_mul_f32_e32 v4, 0x3fb8aa3b, v4
	v_mul_f32_e32 v5, 0x3fb8aa3b, v5
	v_exp_f32_e32 v4, v4
	v_exp_f32_e32 v5, v5
	v_add_f32_e32 v4, 1.0, v4
	v_add_f32_e32 v5, 1.0, v5
	v_rcp_f32_e32 v4, v4
	v_rcp_f32_e32 v5, v5
	s_nop 0
	v_pk_mul_f32 v[2:3], v[2:3], v[4:5]
	s_nop 0
	v_cvt_pk_bf16_f32 v1, v2, v3
	v_mad_i64_i32 v[2:3], s[6:7], v204, s35, v[148:149]
	global_store_dwordx2 v[2:3], v[0:1], off
	ds_read_b128 v[0:3], v236 offset:4352
	ds_read_b128 v[4:7], v236 offset:4416
	s_waitcnt lgkmcnt(1)
	v_mfma_f32_16x16x32_bf16 v[0:3], v[80:83], v[0:3], 0
	s_waitcnt lgkmcnt(0)
	v_mfma_f32_16x16x32_bf16 v[0:3], v[84:87], v[4:7], v[0:3]
	ds_read_b128 v[4:7], v236 offset:4480
	s_waitcnt lgkmcnt(0)
	v_mfma_f32_16x16x32_bf16 v[0:3], v[88:91], v[4:7], v[0:3]
	ds_read_b128 v[4:7], v236 offset:4544
	s_waitcnt lgkmcnt(0)
	v_mfma_f32_16x16x32_bf16 v[0:3], v[92:95], v[4:7], v[0:3]
	s_waitcnt vmcnt(1)
	v_lshlrev_b32_e32 v4, 16, v202
	v_and_b32_e32 v5, 0xffff0000, v202
	s_nop 4
	v_pk_fma_f32 v[0:1], v[96:97], v[4:5], v[0:1]
	s_nop 0
	v_mul_f32_e32 v4, 0x3d372713, v0
	v_mul_f32_e32 v5, 0x3d372713, v1
	v_mul_f32_e32 v4, v0, v4
	v_mul_f32_e32 v5, v1, v5
	v_fma_f32 v4, v0, v4, v0
	v_fma_f32 v5, v1, v5, v1
	v_mul_f32_e32 v4, 0xbfcc422a, v4
	v_mul_f32_e32 v5, 0xbfcc422a, v5
	v_mul_f32_e32 v4, 0x3fb8aa3b, v4
	v_mul_f32_e32 v5, 0x3fb8aa3b, v5
	v_exp_f32_e32 v4, v4
	v_exp_f32_e32 v5, v5
	v_add_f32_e32 v4, 1.0, v4
	v_add_f32_e32 v5, 1.0, v5
	v_rcp_f32_e32 v4, v4
	v_rcp_f32_e32 v5, v5
	s_nop 0
	v_pk_mul_f32 v[0:1], v[0:1], v[4:5]
	v_lshlrev_b32_e32 v4, 16, v203
	v_and_b32_e32 v5, 0xffff0000, v203
	v_pk_fma_f32 v[2:3], v[98:99], v[4:5], v[2:3]
	v_cvt_pk_bf16_f32 v0, v0, v1
	v_mul_f32_e32 v4, 0x3d372713, v2
	v_mul_f32_e32 v5, 0x3d372713, v3
	v_mul_f32_e32 v4, v2, v4
	v_mul_f32_e32 v5, v3, v5
	v_fma_f32 v4, v2, v4, v2
	v_fma_f32 v5, v3, v5, v3
	v_mul_f32_e32 v4, 0xbfcc422a, v4
	v_mul_f32_e32 v5, 0xbfcc422a, v5
	v_mul_f32_e32 v4, 0x3fb8aa3b, v4
	v_mul_f32_e32 v5, 0x3fb8aa3b, v5
	v_exp_f32_e32 v4, v4
	v_exp_f32_e32 v5, v5
	v_add_f32_e32 v4, 1.0, v4
	v_add_f32_e32 v5, 1.0, v5
	v_rcp_f32_e32 v4, v4
	v_rcp_f32_e32 v5, v5
	s_nop 0
	v_pk_mul_f32 v[2:3], v[2:3], v[4:5]
	s_nop 0
	v_cvt_pk_bf16_f32 v1, v2, v3
	v_mad_i64_i32 v[2:3], s[6:7], v200, s35, v[148:149]
	global_store_dwordx2 v[2:3], v[0:1], off
	s_waitcnt lgkmcnt(0)
	s_mov_b64 s[6:7], 0
	s_cbranch_vccz .LBB0_185
	s_add_i32 s10, s10, 1
	s_cmp_eq_u32 s10, 4
	s_cbranch_scc0 .LBB0_184
	s_cmp_eq_u32 s33, 0x100
	s_cbranch_scc0 .Ls5_gen1
	s_add_i32 s4, s4, 8
	s_add_i32 s8, s8, 8
	v_readlane_b32 s6, v255, 29
	s_mul_i32 s6, s6, 12
	s_sub_i32 s6, s4, s6
	s_cmp_gt_i32 s6, 11
	s_cbranch_scc0 .LBB0_179
	s_branch .LBB0_188
.Ls5_gen1:
	s_add_i32 s4, s4, s34
	s_sub_i32 s8, s8, s34
	s_cmpk_gt_i32 s4, 0xbff
	s_cbranch_scc0 .LBB0_179
